# GLA scan: role split - waves 4-7 stream operands, waves 0-3 compute and store the inter-chunk output for both slices (loads and stores in separate wave queues), 16-byte o stores
# speedup vs baseline: 1.0147x; 1.0012x over previous
.LBB0_153:
	s_andn2_b64 vcc, exec, s[0:1]
	s_cbranch_vccnz .LBB0_176
	s_cmpk_gt_i32 s2, 0x7f
	s_cbranch_scc1 .LBB0_176
	s_and_b32 s0, s2, 7
	s_lshr_b32 s1, s2, 3
	s_and_b32 s5, s1, 3
	s_lshl_b32 s0, s0, 2
	s_add_i32 s0, s0, s5
	s_lshr_b32 s1, s1, 2
	v_lshrrev_b32_e32 v92, 6, v220
	s_nop 0
	v_readfirstlane_b32 s5, v92
	s_nop 0
	s_and_b32 s7, s5, 3
	s_lshr_b32 s9, s5, 2
	s_movk_i32 s14, 0x110
	s_movk_i32 s15, 0x90
	s_movk_i32 s45, 0x1a00
	v_and_b32_e32 v92, 15, v227
	v_lshrrev_b32_e32 v93, 4, v227
	v_and_b32_e32 v94, 31, v227
	v_lshrrev_b32_e32 v95, 5, v227
	s_mul_i32 s50, s9, 8704
	s_add_i32 s50, s50, 91136
	s_lshl_b32 s51, s7, 6
	s_add_i32 s51, s51, s50
	v_mul_u32_u24_e32 v164, s14, v94
	v_lshl_add_u32 v164, v95, 3, v164
	v_add_u32_e32 v164, s51, v164
	s_lshl_b32 s50, s7, 7
	s_add_i32 s50, s50, 35840
	v_lshlrev_b32_e32 v208, 4, v95
	v_add_u32_e32 v208, s50, v208
	s_mul_i32 s50, s7, 4608
	s_add_i32 s50, s50, 17408
	v_mul_u32_u24_e32 v209, s15, v94
	v_lshl_add_u32 v209, v95, 4, v209
	v_add_u32_e32 v209, s50, v209
	s_mul_i32 s50, s9, 4608
	s_add_i32 s50, s50, 36352
	v_mul_u32_u24_e32 v210, s15, v94
	v_lshl_add_u32 v210, v95, 4, v210
	v_add_u32_e32 v210, s50, v210
	v_mov_b32_e32 v0, 0
	v_mov_b32_e32 v1, 0
	v_mov_b32_e32 v2, 0
	v_mov_b32_e32 v3, 0
	v_mov_b32_e32 v4, 0
	v_mov_b32_e32 v5, 0
	v_mov_b32_e32 v6, 0
	v_mov_b32_e32 v7, 0
	v_mov_b32_e32 v8, 0
	v_mov_b32_e32 v9, 0
	v_mov_b32_e32 v10, 0
	v_mov_b32_e32 v11, 0
	v_mov_b32_e32 v12, 0
	v_mov_b32_e32 v13, 0
	v_mov_b32_e32 v14, 0
	v_mov_b32_e32 v15, 0
	s_mov_b32 s44, 0
	s_cmp_eq_u32 s9, 0
	s_cbranch_scc1 .Lsc_osetup
	s_lshl_b32 s14, s0, 20
	s_add_u32 s24, s92, s14
	s_addc_u32 s25, s93, 0
	s_add_u32 s28, s24, 0x2000000
	s_addc_u32 s29, s25, 0
	s_add_u32 s24, s24, 0x1000
	s_addc_u32 s25, s25, 0
	s_add_u32 s46, s24, 0x2000
	s_addc_u32 s47, s25, 0
	s_add_u32 s28, s28, 0x1000
	s_addc_u32 s29, s29, 0
	s_add_u32 s48, s28, 0x2000
	s_addc_u32 s49, s29, 0
	s_lshl_b32 s14, s0, 15
	s_add_u32 s14, s14, 0x1fdbb400
	s_add_u32 s38, s20, s14
	s_addc_u32 s39, s21, 0
	s_lshl_b32 s14, s0, 21
	s_add_u32 s15, s14, 0x1cdc4000
	s_sub_u32 s14, s14, 0x3000000
	s_add_u32 s14, s14, 0x29c4000
	s_cmp_lt_u32 s0, 24
	s_cselect_b32 s14, s15, s14
	s_lshl_b32 s15, s1, 13
	s_add_u32 s14, s14, s15
	s_add_u32 s14, s14, 0x1000
	s_add_u32 s40, s20, s14
	s_addc_u32 s41, s21, 0
	s_movk_i32 s14, 0x110
	s_movk_i32 s15, 0x90
	v_and_b32_e32 v92, 0xff, v220
	v_lshlrev_b32_e32 v236, 4, v92
	v_and_b32_e32 v93, 31, v92
	v_lshlrev_b32_e32 v239, 4, v93
	v_add_u32_e32 v239, 35840, v239
	v_lshrrev_b32_e32 v93, 4, v92
	v_and_b32_e32 v94, 15, v92
	v_lshlrev_b32_e32 v94, 4, v94
	v_mad_u32_u24 v237, v93, s14, v94
	v_lshrrev_b32_e32 v93, 3, v92
	v_and_b32_e32 v94, 7, v92
	v_lshlrev_b32_e32 v94, 4, v94
	v_mad_u32_u24 v238, v93, s15, v94
	v_add_u32_e32 v166, 36352, v238
	v_add_u32_e32 v238, 17408, v238
	global_load_dwordx4 v[24:27], v236, s[24:25] offset:-4096
	global_load_dwordx4 v[28:31], v236, s[24:25]
	global_load_dwordx4 v[32:35], v236, s[46:47] offset:-4096
	global_load_dwordx4 v[36:39], v236, s[46:47]
	global_load_dwordx4 v[40:43], v236, s[28:29] offset:-4096
	global_load_dwordx4 v[44:47], v236, s[28:29]
	global_load_dwordx4 v[48:51], v236, s[48:49] offset:-4096
	global_load_dwordx4 v[52:55], v236, s[48:49]
	global_load_dwordx4 v[56:59], v236, s[40:41] offset:-4096
	global_load_dwordx4 v[60:63], v236, s[40:41]
	global_load_dwordx4 v[64:67], v239, s[38:39]
	s_add_u32 s24, s24, 0x4000
	s_addc_u32 s25, s25, 0
	s_add_u32 s46, s46, 0x4000
	s_addc_u32 s47, s47, 0
	s_add_u32 s28, s28, 0x4000
	s_addc_u32 s29, s29, 0
	s_add_u32 s48, s48, 0x4000
	s_addc_u32 s49, s49, 0
	s_add_u32 s40, s40, 0x8000
	s_addc_u32 s41, s41, 0
	s_add_u32 s38, s38, 0x200
	s_addc_u32 s39, s39, 0
	global_load_dwordx4 v[68:71], v236, s[24:25] offset:-4096
	global_load_dwordx4 v[72:75], v236, s[24:25]
	global_load_dwordx4 v[76:79], v236, s[46:47] offset:-4096
	global_load_dwordx4 v[80:83], v236, s[46:47]
	global_load_dwordx4 v[84:87], v236, s[28:29] offset:-4096
	global_load_dwordx4 v[88:91], v236, s[28:29]
	global_load_dwordx4 v[92:95], v236, s[48:49] offset:-4096
	global_load_dwordx4 v[144:147], v236, s[48:49]
	global_load_dwordx4 v[148:151], v236, s[40:41] offset:-4096
	global_load_dwordx4 v[152:155], v236, s[40:41]
	global_load_dwordx4 v[156:159], v239, s[38:39]
	s_add_u32 s24, s24, 0x4000
	s_addc_u32 s25, s25, 0
	s_add_u32 s46, s46, 0x4000
	s_addc_u32 s47, s47, 0
	s_add_u32 s28, s28, 0x4000
	s_addc_u32 s29, s29, 0
	s_add_u32 s48, s48, 0x4000
	s_addc_u32 s49, s49, 0
	s_add_u32 s40, s40, 0x8000
	s_addc_u32 s41, s41, 0
	s_add_u32 s38, s38, 0x200
	s_addc_u32 s39, s39, 0
	global_load_dwordx4 v[160:163], v236, s[24:25] offset:-4096
	global_load_dwordx4 v[172:175], v236, s[24:25]
	global_load_dwordx4 v[180:183], v236, s[46:47] offset:-4096
	global_load_dwordx4 v[184:187], v236, s[46:47]
	global_load_dwordx4 v[188:191], v236, s[28:29] offset:-4096
	global_load_dwordx4 v[192:195], v236, s[28:29]
	global_load_dwordx4 v[196:199], v236, s[48:49] offset:-4096
	global_load_dwordx4 v[200:203], v236, s[48:49]
	global_load_dwordx4 v[204:207], v236, s[40:41] offset:-4096
	global_load_dwordx4 v[212:215], v236, s[40:41]
	global_load_dwordx4 v[216:219], v239, s[38:39]
	s_add_u32 s24, s24, 0x4000
	s_addc_u32 s25, s25, 0
	s_add_u32 s46, s46, 0x4000
	s_addc_u32 s47, s47, 0
	s_add_u32 s28, s28, 0x4000
	s_addc_u32 s29, s29, 0
	s_add_u32 s48, s48, 0x4000
	s_addc_u32 s49, s49, 0
	s_add_u32 s40, s40, 0x8000
	s_addc_u32 s41, s41, 0
	s_add_u32 s38, s38, 0x200
	s_addc_u32 s39, s39, 0
	s_waitcnt vmcnt(22)
	ds_write_b128 v237, v[24:27] offset:0
	ds_write_b128 v237, v[28:31] offset:4352
	ds_write_b128 v237, v[32:35] offset:8704
	ds_write_b128 v237, v[36:39] offset:13056
	ds_write_b128 v238, v[40:43] offset:0
	ds_write_b128 v238, v[44:47] offset:4608
	ds_write_b128 v238, v[48:51] offset:9216
	ds_write_b128 v238, v[52:55] offset:13824
	ds_write_b128 v166, v[56:59] offset:0
	ds_write_b128 v166, v[60:63] offset:4608
	ds_write_b128 v239, v[64:67] offset:0
	s_waitcnt lgkmcnt(0)
	s_barrier
.Lsc_lloop:
.Lsc_lbody0:
	global_load_dwordx4 v[24:27], v236, s[24:25] offset:-4096
	global_load_dwordx4 v[28:31], v236, s[24:25]
	global_load_dwordx4 v[32:35], v236, s[46:47] offset:-4096
	global_load_dwordx4 v[36:39], v236, s[46:47]
	global_load_dwordx4 v[40:43], v236, s[28:29] offset:-4096
	global_load_dwordx4 v[44:47], v236, s[28:29]
	global_load_dwordx4 v[48:51], v236, s[48:49] offset:-4096
	global_load_dwordx4 v[52:55], v236, s[48:49]
	global_load_dwordx4 v[56:59], v236, s[40:41] offset:-4096
	global_load_dwordx4 v[60:63], v236, s[40:41]
	global_load_dwordx4 v[64:67], v239, s[38:39]
	s_add_u32 s24, s24, 0x4000
	s_addc_u32 s25, s25, 0
	s_add_u32 s46, s46, 0x4000
	s_addc_u32 s47, s47, 0
	s_add_u32 s28, s28, 0x4000
	s_addc_u32 s29, s29, 0
	s_add_u32 s48, s48, 0x4000
	s_addc_u32 s49, s49, 0
	s_add_u32 s40, s40, 0x8000
	s_addc_u32 s41, s41, 0
	s_add_u32 s38, s38, 0x200
	s_addc_u32 s39, s39, 0
	v_cvt_pk_bf16_f32 v16, v0, v1
	v_cvt_pk_bf16_f32 v17, v2, v3
	v_cvt_pk_bf16_f32 v18, v4, v5
	v_cvt_pk_bf16_f32 v19, v6, v7
	v_cvt_pk_bf16_f32 v20, v8, v9
	v_cvt_pk_bf16_f32 v21, v10, v11
	v_cvt_pk_bf16_f32 v22, v12, v13
	v_cvt_pk_bf16_f32 v23, v14, v15
	ds_write_b64 v164, v[16:17] offset:0
	ds_write_b64 v164, v[18:19] offset:16
	ds_write_b64 v164, v[20:21] offset:32
	ds_write_b64 v164, v[22:23] offset:48
	ds_read_b128 v[128:131], v208 offset:0
	ds_read_b128 v[132:135], v208 offset:32
	ds_read_b128 v[136:139], v208 offset:64
	ds_read_b128 v[140:143], v208 offset:96
	ds_read_b128 v[96:99], v209 offset:0
	ds_read_b128 v[100:103], v209 offset:32
	ds_read_b128 v[104:107], v209 offset:64
	ds_read_b128 v[108:111], v209 offset:96
	ds_read_b128 v[112:115], v210 offset:0
	ds_read_b128 v[116:119], v210 offset:32
	ds_read_b128 v[120:123], v210 offset:64
	ds_read_b128 v[124:127], v210 offset:96
	s_waitcnt lgkmcnt(8)
	v_mul_f32_e32 v0, v0, v128
	v_mul_f32_e32 v1, v1, v129
	v_mul_f32_e32 v2, v2, v130
	v_mul_f32_e32 v3, v3, v131
	v_mul_f32_e32 v4, v4, v132
	v_mul_f32_e32 v5, v5, v133
	v_mul_f32_e32 v6, v6, v134
	v_mul_f32_e32 v7, v7, v135
	v_mul_f32_e32 v8, v8, v136
	v_mul_f32_e32 v9, v9, v137
	v_mul_f32_e32 v10, v10, v138
	v_mul_f32_e32 v11, v11, v139
	v_mul_f32_e32 v12, v12, v140
	v_mul_f32_e32 v13, v13, v141
	v_mul_f32_e32 v14, v14, v142
	v_mul_f32_e32 v15, v15, v143
	s_waitcnt lgkmcnt(0)
	v_mfma_f32_32x32x16_bf16 v[0:15], v[96:99], v[112:115], v[0:15]
	v_mfma_f32_32x32x16_bf16 v[0:15], v[100:103], v[116:119], v[0:15]
	v_mfma_f32_32x32x16_bf16 v[0:15], v[104:107], v[120:123], v[0:15]
	v_mfma_f32_32x32x16_bf16 v[0:15], v[108:111], v[124:127], v[0:15]
	s_waitcnt vmcnt(22)
	ds_write_b128 v237, v[68:71] offset:45568
	ds_write_b128 v237, v[72:75] offset:49920
	ds_write_b128 v237, v[76:79] offset:54272
	ds_write_b128 v237, v[80:83] offset:58624
	ds_write_b128 v238, v[84:87] offset:45568
	ds_write_b128 v238, v[88:91] offset:50176
	ds_write_b128 v238, v[92:95] offset:54784
	ds_write_b128 v238, v[144:147] offset:59392
	ds_write_b128 v166, v[148:151] offset:45568
	ds_write_b128 v166, v[152:155] offset:50176
	ds_write_b128 v239, v[156:159] offset:45568
	s_add_i32 s44, s44, 1
	s_waitcnt lgkmcnt(0)
	s_barrier
.Lsc_lbody1:
	s_cmp_lt_u32 s44, 61
	s_cbranch_scc0 .Lsc_nold_lk1
	global_load_dwordx4 v[68:71], v236, s[24:25] offset:-4096
	global_load_dwordx4 v[72:75], v236, s[24:25]
	global_load_dwordx4 v[76:79], v236, s[46:47] offset:-4096
	global_load_dwordx4 v[80:83], v236, s[46:47]
	global_load_dwordx4 v[84:87], v236, s[28:29] offset:-4096
	global_load_dwordx4 v[88:91], v236, s[28:29]
	global_load_dwordx4 v[92:95], v236, s[48:49] offset:-4096
	global_load_dwordx4 v[144:147], v236, s[48:49]
	global_load_dwordx4 v[148:151], v236, s[40:41] offset:-4096
	global_load_dwordx4 v[152:155], v236, s[40:41]
	global_load_dwordx4 v[156:159], v239, s[38:39]
	s_add_u32 s24, s24, 0x4000
	s_addc_u32 s25, s25, 0
	s_add_u32 s46, s46, 0x4000
	s_addc_u32 s47, s47, 0
	s_add_u32 s28, s28, 0x4000
	s_addc_u32 s29, s29, 0
	s_add_u32 s48, s48, 0x4000
	s_addc_u32 s49, s49, 0
	s_add_u32 s40, s40, 0x8000
	s_addc_u32 s41, s41, 0
	s_add_u32 s38, s38, 0x200
	s_addc_u32 s39, s39, 0
.Lsc_nold_lk1:
	v_cvt_pk_bf16_f32 v16, v0, v1
	v_cvt_pk_bf16_f32 v17, v2, v3
	v_cvt_pk_bf16_f32 v18, v4, v5
	v_cvt_pk_bf16_f32 v19, v6, v7
	v_cvt_pk_bf16_f32 v20, v8, v9
	v_cvt_pk_bf16_f32 v21, v10, v11
	v_cvt_pk_bf16_f32 v22, v12, v13
	v_cvt_pk_bf16_f32 v23, v14, v15
	ds_write_b64 v164, v[16:17] offset:17408
	ds_write_b64 v164, v[18:19] offset:17424
	ds_write_b64 v164, v[20:21] offset:17440
	ds_write_b64 v164, v[22:23] offset:17456
	ds_read_b128 v[128:131], v208 offset:45568
	ds_read_b128 v[132:135], v208 offset:45600
	ds_read_b128 v[136:139], v208 offset:45632
	ds_read_b128 v[140:143], v208 offset:45664
	ds_read_b128 v[96:99], v209 offset:45568
	ds_read_b128 v[100:103], v209 offset:45600
	ds_read_b128 v[104:107], v209 offset:45632
	ds_read_b128 v[108:111], v209 offset:45664
	ds_read_b128 v[112:115], v210 offset:45568
	ds_read_b128 v[116:119], v210 offset:45600
	ds_read_b128 v[120:123], v210 offset:45632
	ds_read_b128 v[124:127], v210 offset:45664
	s_waitcnt lgkmcnt(8)
	v_mul_f32_e32 v0, v0, v128
	v_mul_f32_e32 v1, v1, v129
	v_mul_f32_e32 v2, v2, v130
	v_mul_f32_e32 v3, v3, v131
	v_mul_f32_e32 v4, v4, v132
	v_mul_f32_e32 v5, v5, v133
	v_mul_f32_e32 v6, v6, v134
	v_mul_f32_e32 v7, v7, v135
	v_mul_f32_e32 v8, v8, v136
	v_mul_f32_e32 v9, v9, v137
	v_mul_f32_e32 v10, v10, v138
	v_mul_f32_e32 v11, v11, v139
	v_mul_f32_e32 v12, v12, v140
	v_mul_f32_e32 v13, v13, v141
	v_mul_f32_e32 v14, v14, v142
	v_mul_f32_e32 v15, v15, v143
	s_waitcnt lgkmcnt(0)
	v_mfma_f32_32x32x16_bf16 v[0:15], v[96:99], v[112:115], v[0:15]
	v_mfma_f32_32x32x16_bf16 v[0:15], v[100:103], v[116:119], v[0:15]
	v_mfma_f32_32x32x16_bf16 v[0:15], v[104:107], v[120:123], v[0:15]
	v_mfma_f32_32x32x16_bf16 v[0:15], v[108:111], v[124:127], v[0:15]
	s_cmp_lt_u32 s44, 61
	s_cbranch_scc1 .Lsc_w22_lk1
	s_waitcnt vmcnt(0)
	s_branch .Lsc_wd_lk1
.Lsc_w22_lk1:
	s_waitcnt vmcnt(22)
.Lsc_wd_lk1:
	ds_write_b128 v237, v[160:163] offset:0
	ds_write_b128 v237, v[172:175] offset:4352
	ds_write_b128 v237, v[180:183] offset:8704
	ds_write_b128 v237, v[184:187] offset:13056
	ds_write_b128 v238, v[188:191] offset:0
	ds_write_b128 v238, v[192:195] offset:4608
	ds_write_b128 v238, v[196:199] offset:9216
	ds_write_b128 v238, v[200:203] offset:13824
	ds_write_b128 v166, v[204:207] offset:0
	ds_write_b128 v166, v[212:215] offset:4608
	ds_write_b128 v239, v[216:219] offset:0
	s_add_i32 s44, s44, 1
	s_waitcnt lgkmcnt(0)
	s_barrier
.Lsc_lbody2:
	s_cmp_lt_u32 s44, 61
	s_cbranch_scc0 .Lsc_nold_lk2
	global_load_dwordx4 v[160:163], v236, s[24:25] offset:-4096
	global_load_dwordx4 v[172:175], v236, s[24:25]
	global_load_dwordx4 v[180:183], v236, s[46:47] offset:-4096
	global_load_dwordx4 v[184:187], v236, s[46:47]
	global_load_dwordx4 v[188:191], v236, s[28:29] offset:-4096
	global_load_dwordx4 v[192:195], v236, s[28:29]
	global_load_dwordx4 v[196:199], v236, s[48:49] offset:-4096
	global_load_dwordx4 v[200:203], v236, s[48:49]
	global_load_dwordx4 v[204:207], v236, s[40:41] offset:-4096
	global_load_dwordx4 v[212:215], v236, s[40:41]
	global_load_dwordx4 v[216:219], v239, s[38:39]
	s_add_u32 s24, s24, 0x4000
	s_addc_u32 s25, s25, 0
	s_add_u32 s46, s46, 0x4000
	s_addc_u32 s47, s47, 0
	s_add_u32 s28, s28, 0x4000
	s_addc_u32 s29, s29, 0
	s_add_u32 s48, s48, 0x4000
	s_addc_u32 s49, s49, 0
	s_add_u32 s40, s40, 0x8000
	s_addc_u32 s41, s41, 0
	s_add_u32 s38, s38, 0x200
	s_addc_u32 s39, s39, 0
.Lsc_nold_lk2:
	v_cvt_pk_bf16_f32 v16, v0, v1
	v_cvt_pk_bf16_f32 v17, v2, v3
	v_cvt_pk_bf16_f32 v18, v4, v5
	v_cvt_pk_bf16_f32 v19, v6, v7
	v_cvt_pk_bf16_f32 v20, v8, v9
	v_cvt_pk_bf16_f32 v21, v10, v11
	v_cvt_pk_bf16_f32 v22, v12, v13
	v_cvt_pk_bf16_f32 v23, v14, v15
	ds_write_b64 v164, v[16:17] offset:0
	ds_write_b64 v164, v[18:19] offset:16
	ds_write_b64 v164, v[20:21] offset:32
	ds_write_b64 v164, v[22:23] offset:48
	ds_read_b128 v[128:131], v208 offset:0
	ds_read_b128 v[132:135], v208 offset:32
	ds_read_b128 v[136:139], v208 offset:64
	ds_read_b128 v[140:143], v208 offset:96
	ds_read_b128 v[96:99], v209 offset:0
	ds_read_b128 v[100:103], v209 offset:32
	ds_read_b128 v[104:107], v209 offset:64
	ds_read_b128 v[108:111], v209 offset:96
	ds_read_b128 v[112:115], v210 offset:0
	ds_read_b128 v[116:119], v210 offset:32
	ds_read_b128 v[120:123], v210 offset:64
	ds_read_b128 v[124:127], v210 offset:96
	s_waitcnt lgkmcnt(8)
	v_mul_f32_e32 v0, v0, v128
	v_mul_f32_e32 v1, v1, v129
	v_mul_f32_e32 v2, v2, v130
	v_mul_f32_e32 v3, v3, v131
	v_mul_f32_e32 v4, v4, v132
	v_mul_f32_e32 v5, v5, v133
	v_mul_f32_e32 v6, v6, v134
	v_mul_f32_e32 v7, v7, v135
	v_mul_f32_e32 v8, v8, v136
	v_mul_f32_e32 v9, v9, v137
	v_mul_f32_e32 v10, v10, v138
	v_mul_f32_e32 v11, v11, v139
	v_mul_f32_e32 v12, v12, v140
	v_mul_f32_e32 v13, v13, v141
	v_mul_f32_e32 v14, v14, v142
	v_mul_f32_e32 v15, v15, v143
	s_waitcnt lgkmcnt(0)
	v_mfma_f32_32x32x16_bf16 v[0:15], v[96:99], v[112:115], v[0:15]
	v_mfma_f32_32x32x16_bf16 v[0:15], v[100:103], v[116:119], v[0:15]
	v_mfma_f32_32x32x16_bf16 v[0:15], v[104:107], v[120:123], v[0:15]
	v_mfma_f32_32x32x16_bf16 v[0:15], v[108:111], v[124:127], v[0:15]
	s_cmp_lt_u32 s44, 61
	s_cbranch_scc1 .Lsc_w22_lk2
	s_waitcnt vmcnt(0)
	s_branch .Lsc_wd_lk2

.Lsc_wd_lk2:
	ds_write_b128 v237, v[24:27] offset:45568
	ds_write_b128 v237, v[28:31] offset:49920
	ds_write_b128 v237, v[32:35] offset:54272
	ds_write_b128 v237, v[36:39] offset:58624
	ds_write_b128 v238, v[40:43] offset:45568
	ds_write_b128 v238, v[44:47] offset:50176
	ds_write_b128 v238, v[48:51] offset:54784
	ds_write_b128 v238, v[52:55] offset:59392
	ds_write_b128 v166, v[56:59] offset:45568
	ds_write_b128 v166, v[60:63] offset:50176
	ds_write_b128 v239, v[64:67] offset:45568
	s_add_i32 s44, s44, 1
	s_waitcnt lgkmcnt(0)
	s_barrier
.Lsc_lbody3:
	s_cmp_lt_u32 s44, 61
	s_cbranch_scc0 .Lsc_nold_lk3
	global_load_dwordx4 v[24:27], v236, s[24:25] offset:-4096
	global_load_dwordx4 v[28:31], v236, s[24:25]
	global_load_dwordx4 v[32:35], v236, s[46:47] offset:-4096
	global_load_dwordx4 v[36:39], v236, s[46:47]
	global_load_dwordx4 v[40:43], v236, s[28:29] offset:-4096
	global_load_dwordx4 v[44:47], v236, s[28:29]
	global_load_dwordx4 v[48:51], v236, s[48:49] offset:-4096
	global_load_dwordx4 v[52:55], v236, s[48:49]
	global_load_dwordx4 v[56:59], v236, s[40:41] offset:-4096
	global_load_dwordx4 v[60:63], v236, s[40:41]
	global_load_dwordx4 v[64:67], v239, s[38:39]
	s_add_u32 s24, s24, 0x4000
	s_addc_u32 s25, s25, 0
	s_add_u32 s46, s46, 0x4000
	s_addc_u32 s47, s47, 0
	s_add_u32 s28, s28, 0x4000
	s_addc_u32 s29, s29, 0
	s_add_u32 s48, s48, 0x4000
	s_addc_u32 s49, s49, 0
	s_add_u32 s40, s40, 0x8000
	s_addc_u32 s41, s41, 0
	s_add_u32 s38, s38, 0x200
	s_addc_u32 s39, s39, 0
.Lsc_nold_lk3:
	v_cvt_pk_bf16_f32 v16, v0, v1
	v_cvt_pk_bf16_f32 v17, v2, v3
	v_cvt_pk_bf16_f32 v18, v4, v5
	v_cvt_pk_bf16_f32 v19, v6, v7
	v_cvt_pk_bf16_f32 v20, v8, v9
	v_cvt_pk_bf16_f32 v21, v10, v11
	v_cvt_pk_bf16_f32 v22, v12, v13
	v_cvt_pk_bf16_f32 v23, v14, v15
	ds_write_b64 v164, v[16:17] offset:17408
	ds_write_b64 v164, v[18:19] offset:17424
	ds_write_b64 v164, v[20:21] offset:17440
	ds_write_b64 v164, v[22:23] offset:17456
	ds_read_b128 v[128:131], v208 offset:45568
	ds_read_b128 v[132:135], v208 offset:45600
	ds_read_b128 v[136:139], v208 offset:45632
	ds_read_b128 v[140:143], v208 offset:45664
	ds_read_b128 v[96:99], v209 offset:45568
	ds_read_b128 v[100:103], v209 offset:45600
	ds_read_b128 v[104:107], v209 offset:45632
	ds_read_b128 v[108:111], v209 offset:45664
	ds_read_b128 v[112:115], v210 offset:45568
	ds_read_b128 v[116:119], v210 offset:45600
	ds_read_b128 v[120:123], v210 offset:45632
	ds_read_b128 v[124:127], v210 offset:45664
	s_waitcnt lgkmcnt(8)
	v_mul_f32_e32 v0, v0, v128
	v_mul_f32_e32 v1, v1, v129
	v_mul_f32_e32 v2, v2, v130
	v_mul_f32_e32 v3, v3, v131
	v_mul_f32_e32 v4, v4, v132
	v_mul_f32_e32 v5, v5, v133
	v_mul_f32_e32 v6, v6, v134
	v_mul_f32_e32 v7, v7, v135
	v_mul_f32_e32 v8, v8, v136
	v_mul_f32_e32 v9, v9, v137
	v_mul_f32_e32 v10, v10, v138
	v_mul_f32_e32 v11, v11, v139
	v_mul_f32_e32 v12, v12, v140
	v_mul_f32_e32 v13, v13, v141
	v_mul_f32_e32 v14, v14, v142
	v_mul_f32_e32 v15, v15, v143
	s_waitcnt lgkmcnt(0)
	v_mfma_f32_32x32x16_bf16 v[0:15], v[96:99], v[112:115], v[0:15]
	v_mfma_f32_32x32x16_bf16 v[0:15], v[100:103], v[116:119], v[0:15]
	v_mfma_f32_32x32x16_bf16 v[0:15], v[104:107], v[120:123], v[0:15]
	v_mfma_f32_32x32x16_bf16 v[0:15], v[108:111], v[124:127], v[0:15]
	s_cmp_lt_u32 s44, 63
	s_cbranch_scc0 .Lsc_nostage_lk3
	s_cmp_lt_u32 s44, 61
	s_cbranch_scc1 .Lsc_w22_lk3
	s_waitcnt vmcnt(0)
	s_branch .Lsc_wd_lk3

.Lsc_wd_lk3:
	ds_write_b128 v237, v[68:71] offset:0
	ds_write_b128 v237, v[72:75] offset:4352
	ds_write_b128 v237, v[76:79] offset:8704
	ds_write_b128 v237, v[80:83] offset:13056
	ds_write_b128 v238, v[84:87] offset:0
	ds_write_b128 v238, v[88:91] offset:4608
	ds_write_b128 v238, v[92:95] offset:9216
	ds_write_b128 v238, v[144:147] offset:13824
	ds_write_b128 v166, v[148:151] offset:0
	ds_write_b128 v166, v[152:155] offset:4608
	ds_write_b128 v239, v[156:159] offset:0
.Lsc_nostage_lk3:
	s_add_i32 s44, s44, 1
	s_waitcnt lgkmcnt(0)
	s_barrier
	s_cmp_eq_u32 s44, 64
	s_cbranch_scc1 .Lsc_lepi
.Lsc_lbody4:
	global_load_dwordx4 v[68:71], v236, s[24:25] offset:-4096
	global_load_dwordx4 v[72:75], v236, s[24:25]
	global_load_dwordx4 v[76:79], v236, s[46:47] offset:-4096
	global_load_dwordx4 v[80:83], v236, s[46:47]
	global_load_dwordx4 v[84:87], v236, s[28:29] offset:-4096
	global_load_dwordx4 v[88:91], v236, s[28:29]
	global_load_dwordx4 v[92:95], v236, s[48:49] offset:-4096
	global_load_dwordx4 v[144:147], v236, s[48:49]
	global_load_dwordx4 v[148:151], v236, s[40:41] offset:-4096
	global_load_dwordx4 v[152:155], v236, s[40:41]
	global_load_dwordx4 v[156:159], v239, s[38:39]
	s_add_u32 s24, s24, 0x4000
	s_addc_u32 s25, s25, 0
	s_add_u32 s46, s46, 0x4000
	s_addc_u32 s47, s47, 0
	s_add_u32 s28, s28, 0x4000
	s_addc_u32 s29, s29, 0
	s_add_u32 s48, s48, 0x4000
	s_addc_u32 s49, s49, 0
	s_add_u32 s40, s40, 0x8000
	s_addc_u32 s41, s41, 0
	s_add_u32 s38, s38, 0x200
	s_addc_u32 s39, s39, 0
	v_cvt_pk_bf16_f32 v16, v0, v1
	v_cvt_pk_bf16_f32 v17, v2, v3
	v_cvt_pk_bf16_f32 v18, v4, v5
	v_cvt_pk_bf16_f32 v19, v6, v7
	v_cvt_pk_bf16_f32 v20, v8, v9
	v_cvt_pk_bf16_f32 v21, v10, v11
	v_cvt_pk_bf16_f32 v22, v12, v13
	v_cvt_pk_bf16_f32 v23, v14, v15
	ds_write_b64 v164, v[16:17] offset:0
	ds_write_b64 v164, v[18:19] offset:16
	ds_write_b64 v164, v[20:21] offset:32
	ds_write_b64 v164, v[22:23] offset:48
	ds_read_b128 v[128:131], v208 offset:0
	ds_read_b128 v[132:135], v208 offset:32
	ds_read_b128 v[136:139], v208 offset:64
	ds_read_b128 v[140:143], v208 offset:96
	ds_read_b128 v[96:99], v209 offset:0
	ds_read_b128 v[100:103], v209 offset:32
	ds_read_b128 v[104:107], v209 offset:64
	ds_read_b128 v[108:111], v209 offset:96
	ds_read_b128 v[112:115], v210 offset:0
	ds_read_b128 v[116:119], v210 offset:32
	ds_read_b128 v[120:123], v210 offset:64
	ds_read_b128 v[124:127], v210 offset:96
	s_waitcnt lgkmcnt(8)
	v_mul_f32_e32 v0, v0, v128
	v_mul_f32_e32 v1, v1, v129
	v_mul_f32_e32 v2, v2, v130
	v_mul_f32_e32 v3, v3, v131
	v_mul_f32_e32 v4, v4, v132
	v_mul_f32_e32 v5, v5, v133
	v_mul_f32_e32 v6, v6, v134
	v_mul_f32_e32 v7, v7, v135
	v_mul_f32_e32 v8, v8, v136
	v_mul_f32_e32 v9, v9, v137
	v_mul_f32_e32 v10, v10, v138
	v_mul_f32_e32 v11, v11, v139
	v_mul_f32_e32 v12, v12, v140
	v_mul_f32_e32 v13, v13, v141
	v_mul_f32_e32 v14, v14, v142
	v_mul_f32_e32 v15, v15, v143
	s_waitcnt lgkmcnt(0)
	v_mfma_f32_32x32x16_bf16 v[0:15], v[96:99], v[112:115], v[0:15]
	v_mfma_f32_32x32x16_bf16 v[0:15], v[100:103], v[116:119], v[0:15]
	v_mfma_f32_32x32x16_bf16 v[0:15], v[104:107], v[120:123], v[0:15]
	v_mfma_f32_32x32x16_bf16 v[0:15], v[108:111], v[124:127], v[0:15]
	s_waitcnt vmcnt(22)
	ds_write_b128 v237, v[160:163] offset:45568
	ds_write_b128 v237, v[172:175] offset:49920
	ds_write_b128 v237, v[180:183] offset:54272
	ds_write_b128 v237, v[184:187] offset:58624
	ds_write_b128 v238, v[188:191] offset:45568
	ds_write_b128 v238, v[192:195] offset:50176
	ds_write_b128 v238, v[196:199] offset:54784
	ds_write_b128 v238, v[200:203] offset:59392
	ds_write_b128 v166, v[204:207] offset:45568
	ds_write_b128 v166, v[212:215] offset:50176
	ds_write_b128 v239, v[216:219] offset:45568
	s_add_i32 s44, s44, 1
	s_waitcnt lgkmcnt(0)
	s_barrier
.Lsc_lbody5:
	global_load_dwordx4 v[160:163], v236, s[24:25] offset:-4096
	global_load_dwordx4 v[172:175], v236, s[24:25]
	global_load_dwordx4 v[180:183], v236, s[46:47] offset:-4096
	global_load_dwordx4 v[184:187], v236, s[46:47]
	global_load_dwordx4 v[188:191], v236, s[28:29] offset:-4096
	global_load_dwordx4 v[192:195], v236, s[28:29]
	global_load_dwordx4 v[196:199], v236, s[48:49] offset:-4096
	global_load_dwordx4 v[200:203], v236, s[48:49]
	global_load_dwordx4 v[204:207], v236, s[40:41] offset:-4096
	global_load_dwordx4 v[212:215], v236, s[40:41]
	global_load_dwordx4 v[216:219], v239, s[38:39]
	s_add_u32 s24, s24, 0x4000
	s_addc_u32 s25, s25, 0
	s_add_u32 s46, s46, 0x4000
	s_addc_u32 s47, s47, 0
	s_add_u32 s28, s28, 0x4000
	s_addc_u32 s29, s29, 0
	s_add_u32 s48, s48, 0x4000
	s_addc_u32 s49, s49, 0
	s_add_u32 s40, s40, 0x8000
	s_addc_u32 s41, s41, 0
	s_add_u32 s38, s38, 0x200
	s_addc_u32 s39, s39, 0
	v_cvt_pk_bf16_f32 v16, v0, v1
	v_cvt_pk_bf16_f32 v17, v2, v3
	v_cvt_pk_bf16_f32 v18, v4, v5
	v_cvt_pk_bf16_f32 v19, v6, v7
	v_cvt_pk_bf16_f32 v20, v8, v9
	v_cvt_pk_bf16_f32 v21, v10, v11
	v_cvt_pk_bf16_f32 v22, v12, v13
	v_cvt_pk_bf16_f32 v23, v14, v15
	ds_write_b64 v164, v[16:17] offset:17408
	ds_write_b64 v164, v[18:19] offset:17424
	ds_write_b64 v164, v[20:21] offset:17440
	ds_write_b64 v164, v[22:23] offset:17456
	ds_read_b128 v[128:131], v208 offset:45568
	ds_read_b128 v[132:135], v208 offset:45600
	ds_read_b128 v[136:139], v208 offset:45632
	ds_read_b128 v[140:143], v208 offset:45664
	ds_read_b128 v[96:99], v209 offset:45568
	ds_read_b128 v[100:103], v209 offset:45600
	ds_read_b128 v[104:107], v209 offset:45632
	ds_read_b128 v[108:111], v209 offset:45664
	ds_read_b128 v[112:115], v210 offset:45568
	ds_read_b128 v[116:119], v210 offset:45600
	ds_read_b128 v[120:123], v210 offset:45632
	ds_read_b128 v[124:127], v210 offset:45664
	s_waitcnt lgkmcnt(8)
	v_mul_f32_e32 v0, v0, v128
	v_mul_f32_e32 v1, v1, v129
	v_mul_f32_e32 v2, v2, v130
	v_mul_f32_e32 v3, v3, v131
	v_mul_f32_e32 v4, v4, v132
	v_mul_f32_e32 v5, v5, v133
	v_mul_f32_e32 v6, v6, v134
	v_mul_f32_e32 v7, v7, v135
	v_mul_f32_e32 v8, v8, v136
	v_mul_f32_e32 v9, v9, v137
	v_mul_f32_e32 v10, v10, v138
	v_mul_f32_e32 v11, v11, v139
	v_mul_f32_e32 v12, v12, v140
	v_mul_f32_e32 v13, v13, v141
	v_mul_f32_e32 v14, v14, v142
	v_mul_f32_e32 v15, v15, v143
	s_waitcnt lgkmcnt(0)
	v_mfma_f32_32x32x16_bf16 v[0:15], v[96:99], v[112:115], v[0:15]
	v_mfma_f32_32x32x16_bf16 v[0:15], v[100:103], v[116:119], v[0:15]
	v_mfma_f32_32x32x16_bf16 v[0:15], v[104:107], v[120:123], v[0:15]
	v_mfma_f32_32x32x16_bf16 v[0:15], v[108:111], v[124:127], v[0:15]
	s_waitcnt vmcnt(22)
	ds_write_b128 v237, v[24:27] offset:0
	ds_write_b128 v237, v[28:31] offset:4352
	ds_write_b128 v237, v[32:35] offset:8704
	ds_write_b128 v237, v[36:39] offset:13056
	ds_write_b128 v238, v[40:43] offset:0
	ds_write_b128 v238, v[44:47] offset:4608
	ds_write_b128 v238, v[48:51] offset:9216
	ds_write_b128 v238, v[52:55] offset:13824
	ds_write_b128 v166, v[56:59] offset:0
	ds_write_b128 v166, v[60:63] offset:4608
	ds_write_b128 v239, v[64:67] offset:0
	s_add_i32 s44, s44, 1
	s_waitcnt lgkmcnt(0)
	s_barrier
	s_branch .Lsc_lloop
.Lsc_lepi:
	v_mov_b64_e32 v[166:167], 0x400
	v_mov_b64_e32 v[168:169], 0xff
	s_branch .LBB0_176
.Lsc_osetup:
	s_lshr_b32 s14, s0, 2
	s_mul_i32 s14, s14, 0x1a00000
	s_add_u32 s42, s96, s14
	s_addc_u32 s43, s97, 0
	s_movk_i32 s14, 0x110
	s_lshl_b32 s50, s7, 4
	v_add_u32_e32 v88, s50, v92
	v_mul_u32_u24_e32 v88, s14, v88
	v_lshl_add_u32 v88, v93, 4, v88
	v_add_u32_e32 v90, s50, v92
	v_mul_u32_u24_e32 v90, s45, v90
	s_and_b32 s50, s0, 3
	s_lshl_b32 s50, s50, 9
	s_lshl_b32 s51, s1, 7
	s_add_i32 s50, s50, s51
	v_lshl_add_u32 v90, v93, 4, v90
	v_add_u32_e32 v90, s50, v90
	v_lshrrev_b32_e32 v94, 2, v92
	v_and_b32_e32 v95, 3, v92
	v_lshl_add_u32 v94, v94, 3, v95
	v_mul_u32_u24_e32 v89, s14, v94
	v_lshl_add_u32 v89, v93, 4, v89
	v_add_u32_e32 v89, 91136, v89
	s_barrier
.Lsc_oloop:
.Lsc_obody0:
	v_cvt_pk_bf16_f32 v16, v0, v1
	v_cvt_pk_bf16_f32 v17, v2, v3
	v_cvt_pk_bf16_f32 v18, v4, v5
	v_cvt_pk_bf16_f32 v19, v6, v7
	v_cvt_pk_bf16_f32 v20, v8, v9
	v_cvt_pk_bf16_f32 v21, v10, v11
	v_cvt_pk_bf16_f32 v22, v12, v13
	v_cvt_pk_bf16_f32 v23, v14, v15
	ds_write_b64 v164, v[16:17] offset:0
	ds_write_b64 v164, v[18:19] offset:16
	ds_write_b64 v164, v[20:21] offset:32
	ds_write_b64 v164, v[22:23] offset:48
	ds_read_b128 v[128:131], v208 offset:0
	ds_read_b128 v[132:135], v208 offset:32
	ds_read_b128 v[136:139], v208 offset:64
	ds_read_b128 v[140:143], v208 offset:96
	ds_read_b128 v[96:99], v209 offset:0
	ds_read_b128 v[100:103], v209 offset:32
	ds_read_b128 v[104:107], v209 offset:64
	ds_read_b128 v[108:111], v209 offset:96
	ds_read_b128 v[112:115], v210 offset:0
	ds_read_b128 v[116:119], v210 offset:32
	ds_read_b128 v[120:123], v210 offset:64
	ds_read_b128 v[124:127], v210 offset:96
	s_waitcnt lgkmcnt(8)
	v_mul_f32_e32 v0, v0, v128
	v_mul_f32_e32 v1, v1, v129
	v_mul_f32_e32 v2, v2, v130
	v_mul_f32_e32 v3, v3, v131
	v_mul_f32_e32 v4, v4, v132
	v_mul_f32_e32 v5, v5, v133
	v_mul_f32_e32 v6, v6, v134
	v_mul_f32_e32 v7, v7, v135
	v_mul_f32_e32 v8, v8, v136
	v_mul_f32_e32 v9, v9, v137
	v_mul_f32_e32 v10, v10, v138
	v_mul_f32_e32 v11, v11, v139
	v_mul_f32_e32 v12, v12, v140
	v_mul_f32_e32 v13, v13, v141
	v_mul_f32_e32 v14, v14, v142
	v_mul_f32_e32 v15, v15, v143
	ds_read_b128 v[40:43], v89 offset:17408
	ds_read_b128 v[44:47], v89 offset:17472
	ds_read_b128 v[48:51], v89 offset:17536
	ds_read_b128 v[52:55], v89 offset:17600
	s_waitcnt lgkmcnt(4)
	v_mfma_f32_32x32x16_bf16 v[0:15], v[96:99], v[112:115], v[0:15]
	v_mfma_f32_32x32x16_bf16 v[0:15], v[100:103], v[116:119], v[0:15]
	v_mfma_f32_32x32x16_bf16 v[0:15], v[104:107], v[120:123], v[0:15]
	v_mfma_f32_32x32x16_bf16 v[0:15], v[108:111], v[124:127], v[0:15]
	ds_read_b128 v[128:131], v89 offset:18496
	ds_read_b128 v[132:135], v89 offset:18560
	ds_read_b128 v[136:139], v89 offset:18624
	ds_read_b128 v[140:143], v89 offset:18688
	ds_read_b128 v[56:59], v88 offset:0
	ds_read_b128 v[60:63], v88 offset:64
	ds_read_b128 v[64:67], v88 offset:128
	ds_read_b128 v[68:71], v88 offset:192
	s_waitcnt lgkmcnt(8)
	v_mfma_f32_16x16x32_bf16 v[24:27], v[40:43], v[72:75], 0
	v_mfma_f32_16x16x32_bf16 v[24:27], v[44:47], v[76:79], v[24:27]
	v_mfma_f32_16x16x32_bf16 v[24:27], v[48:51], v[80:83], v[24:27]
	v_mfma_f32_16x16x32_bf16 v[24:27], v[52:55], v[84:87], v[24:27]
	ds_read_b128 v[40:43], v89 offset:26112
	ds_read_b128 v[44:47], v89 offset:26176
	ds_read_b128 v[48:51], v89 offset:26240
	ds_read_b128 v[52:55], v89 offset:26304
	s_waitcnt lgkmcnt(8)
	v_mfma_f32_16x16x32_bf16 v[28:31], v[128:131], v[72:75], 0
	v_mfma_f32_16x16x32_bf16 v[28:31], v[132:135], v[76:79], v[28:31]
	v_mfma_f32_16x16x32_bf16 v[28:31], v[136:139], v[80:83], v[28:31]
	v_mfma_f32_16x16x32_bf16 v[28:31], v[140:143], v[84:87], v[28:31]
	ds_read_b128 v[128:131], v89 offset:27200
	ds_read_b128 v[132:135], v89 offset:27264
	ds_read_b128 v[136:139], v89 offset:27328
	ds_read_b128 v[140:143], v89 offset:27392
	s_waitcnt lgkmcnt(4)
	v_mfma_f32_16x16x32_bf16 v[32:35], v[40:43], v[72:75], 0
	v_mfma_f32_16x16x32_bf16 v[32:35], v[44:47], v[76:79], v[32:35]
	v_mfma_f32_16x16x32_bf16 v[32:35], v[48:51], v[80:83], v[32:35]
	v_mfma_f32_16x16x32_bf16 v[32:35], v[52:55], v[84:87], v[32:35]
	s_waitcnt lgkmcnt(0)
	v_mfma_f32_16x16x32_bf16 v[36:39], v[128:131], v[72:75], 0
	v_mfma_f32_16x16x32_bf16 v[36:39], v[132:135], v[76:79], v[36:39]
	v_mfma_f32_16x16x32_bf16 v[36:39], v[136:139], v[80:83], v[36:39]
	v_mfma_f32_16x16x32_bf16 v[36:39], v[140:143], v[84:87], v[36:39]
	s_cmp_eq_u32 s44, 0
	s_cbranch_scc1 .Lsc_nost_ok0
	v_cvt_pk_bf16_f32 v24, v24, v25
	v_cvt_pk_bf16_f32 v25, v26, v27
	v_cvt_pk_bf16_f32 v26, v28, v29
	v_cvt_pk_bf16_f32 v27, v30, v31
	global_store_dwordx4 v90, v[24:27], s[42:43]
	v_cvt_pk_bf16_f32 v32, v32, v33
	v_cvt_pk_bf16_f32 v33, v34, v35
	s_nop 1
	v_cvt_pk_bf16_f32 v34, v36, v37
	v_cvt_pk_bf16_f32 v35, v38, v39
	global_store_dwordx4 v90, v[32:35], s[42:43] offset:64
	s_add_u32 s42, s42, 0x68000
	s_addc_u32 s43, s43, 0

.Lsc_obody1:
	v_cvt_pk_bf16_f32 v16, v0, v1
	v_cvt_pk_bf16_f32 v17, v2, v3
	v_cvt_pk_bf16_f32 v18, v4, v5
	v_cvt_pk_bf16_f32 v19, v6, v7
	v_cvt_pk_bf16_f32 v20, v8, v9
	v_cvt_pk_bf16_f32 v21, v10, v11
	v_cvt_pk_bf16_f32 v22, v12, v13
	v_cvt_pk_bf16_f32 v23, v14, v15
	ds_write_b64 v164, v[16:17] offset:17408
	ds_write_b64 v164, v[18:19] offset:17424
	ds_write_b64 v164, v[20:21] offset:17440
	ds_write_b64 v164, v[22:23] offset:17456
	ds_read_b128 v[128:131], v208 offset:45568
	ds_read_b128 v[132:135], v208 offset:45600
	ds_read_b128 v[136:139], v208 offset:45632
	ds_read_b128 v[140:143], v208 offset:45664
	ds_read_b128 v[96:99], v209 offset:45568
	ds_read_b128 v[100:103], v209 offset:45600
	ds_read_b128 v[104:107], v209 offset:45632
	ds_read_b128 v[108:111], v209 offset:45664
	ds_read_b128 v[112:115], v210 offset:45568
	ds_read_b128 v[116:119], v210 offset:45600
	ds_read_b128 v[120:123], v210 offset:45632
	ds_read_b128 v[124:127], v210 offset:45664
	s_waitcnt lgkmcnt(8)
	v_mul_f32_e32 v0, v0, v128
	v_mul_f32_e32 v1, v1, v129
	v_mul_f32_e32 v2, v2, v130
	v_mul_f32_e32 v3, v3, v131
	v_mul_f32_e32 v4, v4, v132
	v_mul_f32_e32 v5, v5, v133
	v_mul_f32_e32 v6, v6, v134
	v_mul_f32_e32 v7, v7, v135
	v_mul_f32_e32 v8, v8, v136
	v_mul_f32_e32 v9, v9, v137
	v_mul_f32_e32 v10, v10, v138
	v_mul_f32_e32 v11, v11, v139
	v_mul_f32_e32 v12, v12, v140
	v_mul_f32_e32 v13, v13, v141
	v_mul_f32_e32 v14, v14, v142
	v_mul_f32_e32 v15, v15, v143
	ds_read_b128 v[40:43], v89 offset:0
	ds_read_b128 v[44:47], v89 offset:64
	ds_read_b128 v[48:51], v89 offset:128
	ds_read_b128 v[52:55], v89 offset:192
	s_waitcnt lgkmcnt(4)
	v_mfma_f32_32x32x16_bf16 v[0:15], v[96:99], v[112:115], v[0:15]
	v_mfma_f32_32x32x16_bf16 v[0:15], v[100:103], v[116:119], v[0:15]
	v_mfma_f32_32x32x16_bf16 v[0:15], v[104:107], v[120:123], v[0:15]
	v_mfma_f32_32x32x16_bf16 v[0:15], v[108:111], v[124:127], v[0:15]
	ds_read_b128 v[128:131], v89 offset:1088
	ds_read_b128 v[132:135], v89 offset:1152
	ds_read_b128 v[136:139], v89 offset:1216
	ds_read_b128 v[140:143], v89 offset:1280
	ds_read_b128 v[72:75], v88 offset:45568
	ds_read_b128 v[76:79], v88 offset:45632
	ds_read_b128 v[80:83], v88 offset:45696
	ds_read_b128 v[84:87], v88 offset:45760
	s_waitcnt lgkmcnt(8)
	v_mfma_f32_16x16x32_bf16 v[24:27], v[40:43], v[56:59], 0
	v_mfma_f32_16x16x32_bf16 v[24:27], v[44:47], v[60:63], v[24:27]
	v_mfma_f32_16x16x32_bf16 v[24:27], v[48:51], v[64:67], v[24:27]
	v_mfma_f32_16x16x32_bf16 v[24:27], v[52:55], v[68:71], v[24:27]
	ds_read_b128 v[40:43], v89 offset:8704
	ds_read_b128 v[44:47], v89 offset:8768
	ds_read_b128 v[48:51], v89 offset:8832
	ds_read_b128 v[52:55], v89 offset:8896
	s_waitcnt lgkmcnt(8)
	v_mfma_f32_16x16x32_bf16 v[28:31], v[128:131], v[56:59], 0
	v_mfma_f32_16x16x32_bf16 v[28:31], v[132:135], v[60:63], v[28:31]
	v_mfma_f32_16x16x32_bf16 v[28:31], v[136:139], v[64:67], v[28:31]
	v_mfma_f32_16x16x32_bf16 v[28:31], v[140:143], v[68:71], v[28:31]
	ds_read_b128 v[128:131], v89 offset:9792
	ds_read_b128 v[132:135], v89 offset:9856
	ds_read_b128 v[136:139], v89 offset:9920
	ds_read_b128 v[140:143], v89 offset:9984
	s_waitcnt lgkmcnt(4)
	v_mfma_f32_16x16x32_bf16 v[32:35], v[40:43], v[56:59], 0
	v_mfma_f32_16x16x32_bf16 v[32:35], v[44:47], v[60:63], v[32:35]
	v_mfma_f32_16x16x32_bf16 v[32:35], v[48:51], v[64:67], v[32:35]
	v_mfma_f32_16x16x32_bf16 v[32:35], v[52:55], v[68:71], v[32:35]
	s_waitcnt lgkmcnt(0)
	v_mfma_f32_16x16x32_bf16 v[36:39], v[128:131], v[56:59], 0
	v_mfma_f32_16x16x32_bf16 v[36:39], v[132:135], v[60:63], v[36:39]
	v_mfma_f32_16x16x32_bf16 v[36:39], v[136:139], v[64:67], v[36:39]
	v_mfma_f32_16x16x32_bf16 v[36:39], v[140:143], v[68:71], v[36:39]
	v_cvt_pk_bf16_f32 v24, v24, v25
	v_cvt_pk_bf16_f32 v25, v26, v27
	v_cvt_pk_bf16_f32 v26, v28, v29
	v_cvt_pk_bf16_f32 v27, v30, v31
	global_store_dwordx4 v90, v[24:27], s[42:43]
	v_cvt_pk_bf16_f32 v32, v32, v33
	v_cvt_pk_bf16_f32 v33, v34, v35
	s_nop 1
	v_cvt_pk_bf16_f32 v34, v36, v37
	v_cvt_pk_bf16_f32 v35, v38, v39
	global_store_dwordx4 v90, v[32:35], s[42:43] offset:64
	s_add_u32 s42, s42, 0x68000
	s_addc_u32 s43, s43, 0
	s_add_i32 s44, s44, 1
	s_waitcnt lgkmcnt(0)
	s_barrier
.Lsc_obody2:
	v_cvt_pk_bf16_f32 v16, v0, v1
	v_cvt_pk_bf16_f32 v17, v2, v3
	v_cvt_pk_bf16_f32 v18, v4, v5
	v_cvt_pk_bf16_f32 v19, v6, v7
	v_cvt_pk_bf16_f32 v20, v8, v9
	v_cvt_pk_bf16_f32 v21, v10, v11
	v_cvt_pk_bf16_f32 v22, v12, v13
	v_cvt_pk_bf16_f32 v23, v14, v15
	ds_write_b64 v164, v[16:17] offset:0
	ds_write_b64 v164, v[18:19] offset:16
	ds_write_b64 v164, v[20:21] offset:32
	ds_write_b64 v164, v[22:23] offset:48
	ds_read_b128 v[128:131], v208 offset:0
	ds_read_b128 v[132:135], v208 offset:32
	ds_read_b128 v[136:139], v208 offset:64
	ds_read_b128 v[140:143], v208 offset:96
	ds_read_b128 v[96:99], v209 offset:0
	ds_read_b128 v[100:103], v209 offset:32
	ds_read_b128 v[104:107], v209 offset:64
	ds_read_b128 v[108:111], v209 offset:96
	ds_read_b128 v[112:115], v210 offset:0
	ds_read_b128 v[116:119], v210 offset:32
	ds_read_b128 v[120:123], v210 offset:64
	ds_read_b128 v[124:127], v210 offset:96
	s_waitcnt lgkmcnt(8)
	v_mul_f32_e32 v0, v0, v128
	v_mul_f32_e32 v1, v1, v129
	v_mul_f32_e32 v2, v2, v130
	v_mul_f32_e32 v3, v3, v131
	v_mul_f32_e32 v4, v4, v132
	v_mul_f32_e32 v5, v5, v133
	v_mul_f32_e32 v6, v6, v134
	v_mul_f32_e32 v7, v7, v135
	v_mul_f32_e32 v8, v8, v136
	v_mul_f32_e32 v9, v9, v137
	v_mul_f32_e32 v10, v10, v138
	v_mul_f32_e32 v11, v11, v139
	v_mul_f32_e32 v12, v12, v140
	v_mul_f32_e32 v13, v13, v141
	v_mul_f32_e32 v14, v14, v142
	v_mul_f32_e32 v15, v15, v143
	ds_read_b128 v[40:43], v89 offset:17408
	ds_read_b128 v[44:47], v89 offset:17472
	ds_read_b128 v[48:51], v89 offset:17536
	ds_read_b128 v[52:55], v89 offset:17600
	s_waitcnt lgkmcnt(4)
	v_mfma_f32_32x32x16_bf16 v[0:15], v[96:99], v[112:115], v[0:15]
	v_mfma_f32_32x32x16_bf16 v[0:15], v[100:103], v[116:119], v[0:15]
	v_mfma_f32_32x32x16_bf16 v[0:15], v[104:107], v[120:123], v[0:15]
	v_mfma_f32_32x32x16_bf16 v[0:15], v[108:111], v[124:127], v[0:15]
	ds_read_b128 v[128:131], v89 offset:18496
	ds_read_b128 v[132:135], v89 offset:18560
	ds_read_b128 v[136:139], v89 offset:18624
	ds_read_b128 v[140:143], v89 offset:18688
	ds_read_b128 v[56:59], v88 offset:0
	ds_read_b128 v[60:63], v88 offset:64
	ds_read_b128 v[64:67], v88 offset:128
	ds_read_b128 v[68:71], v88 offset:192
	s_waitcnt lgkmcnt(8)
	v_mfma_f32_16x16x32_bf16 v[24:27], v[40:43], v[72:75], 0
	v_mfma_f32_16x16x32_bf16 v[24:27], v[44:47], v[76:79], v[24:27]
	v_mfma_f32_16x16x32_bf16 v[24:27], v[48:51], v[80:83], v[24:27]
	v_mfma_f32_16x16x32_bf16 v[24:27], v[52:55], v[84:87], v[24:27]
	ds_read_b128 v[40:43], v89 offset:26112
	ds_read_b128 v[44:47], v89 offset:26176
	ds_read_b128 v[48:51], v89 offset:26240
	ds_read_b128 v[52:55], v89 offset:26304
	s_waitcnt lgkmcnt(8)
	v_mfma_f32_16x16x32_bf16 v[28:31], v[128:131], v[72:75], 0
	v_mfma_f32_16x16x32_bf16 v[28:31], v[132:135], v[76:79], v[28:31]
	v_mfma_f32_16x16x32_bf16 v[28:31], v[136:139], v[80:83], v[28:31]
	v_mfma_f32_16x16x32_bf16 v[28:31], v[140:143], v[84:87], v[28:31]
	ds_read_b128 v[128:131], v89 offset:27200
	ds_read_b128 v[132:135], v89 offset:27264
	ds_read_b128 v[136:139], v89 offset:27328
	ds_read_b128 v[140:143], v89 offset:27392
	s_waitcnt lgkmcnt(4)
	v_mfma_f32_16x16x32_bf16 v[32:35], v[40:43], v[72:75], 0
	v_mfma_f32_16x16x32_bf16 v[32:35], v[44:47], v[76:79], v[32:35]
	v_mfma_f32_16x16x32_bf16 v[32:35], v[48:51], v[80:83], v[32:35]
	v_mfma_f32_16x16x32_bf16 v[32:35], v[52:55], v[84:87], v[32:35]
	s_waitcnt lgkmcnt(0)
	v_mfma_f32_16x16x32_bf16 v[36:39], v[128:131], v[72:75], 0
	v_mfma_f32_16x16x32_bf16 v[36:39], v[132:135], v[76:79], v[36:39]
	v_mfma_f32_16x16x32_bf16 v[36:39], v[136:139], v[80:83], v[36:39]
	v_mfma_f32_16x16x32_bf16 v[36:39], v[140:143], v[84:87], v[36:39]
	v_cvt_pk_bf16_f32 v24, v24, v25
	v_cvt_pk_bf16_f32 v25, v26, v27
	v_cvt_pk_bf16_f32 v26, v28, v29
	v_cvt_pk_bf16_f32 v27, v30, v31
	global_store_dwordx4 v90, v[24:27], s[42:43]
	v_cvt_pk_bf16_f32 v32, v32, v33
	v_cvt_pk_bf16_f32 v33, v34, v35
	s_nop 1
	v_cvt_pk_bf16_f32 v34, v36, v37
	v_cvt_pk_bf16_f32 v35, v38, v39
	global_store_dwordx4 v90, v[32:35], s[42:43] offset:64
	s_add_u32 s42, s42, 0x68000
	s_addc_u32 s43, s43, 0
	s_add_i32 s44, s44, 1
	s_waitcnt lgkmcnt(0)
	s_barrier
.Lsc_obody3:
	v_cvt_pk_bf16_f32 v16, v0, v1
	v_cvt_pk_bf16_f32 v17, v2, v3
	v_cvt_pk_bf16_f32 v18, v4, v5
	v_cvt_pk_bf16_f32 v19, v6, v7
	v_cvt_pk_bf16_f32 v20, v8, v9
	v_cvt_pk_bf16_f32 v21, v10, v11
	v_cvt_pk_bf16_f32 v22, v12, v13
	v_cvt_pk_bf16_f32 v23, v14, v15
	ds_write_b64 v164, v[16:17] offset:17408
	ds_write_b64 v164, v[18:19] offset:17424
	ds_write_b64 v164, v[20:21] offset:17440
	ds_write_b64 v164, v[22:23] offset:17456
	ds_read_b128 v[128:131], v208 offset:45568
	ds_read_b128 v[132:135], v208 offset:45600
	ds_read_b128 v[136:139], v208 offset:45632
	ds_read_b128 v[140:143], v208 offset:45664
	ds_read_b128 v[96:99], v209 offset:45568
	ds_read_b128 v[100:103], v209 offset:45600
	ds_read_b128 v[104:107], v209 offset:45632
	ds_read_b128 v[108:111], v209 offset:45664
	ds_read_b128 v[112:115], v210 offset:45568
	ds_read_b128 v[116:119], v210 offset:45600
	ds_read_b128 v[120:123], v210 offset:45632
	ds_read_b128 v[124:127], v210 offset:45664
	s_waitcnt lgkmcnt(8)
	v_mul_f32_e32 v0, v0, v128
	v_mul_f32_e32 v1, v1, v129
	v_mul_f32_e32 v2, v2, v130
	v_mul_f32_e32 v3, v3, v131
	v_mul_f32_e32 v4, v4, v132
	v_mul_f32_e32 v5, v5, v133
	v_mul_f32_e32 v6, v6, v134
	v_mul_f32_e32 v7, v7, v135
	v_mul_f32_e32 v8, v8, v136
	v_mul_f32_e32 v9, v9, v137
	v_mul_f32_e32 v10, v10, v138
	v_mul_f32_e32 v11, v11, v139
	v_mul_f32_e32 v12, v12, v140
	v_mul_f32_e32 v13, v13, v141
	v_mul_f32_e32 v14, v14, v142
	v_mul_f32_e32 v15, v15, v143
	ds_read_b128 v[40:43], v89 offset:0
	ds_read_b128 v[44:47], v89 offset:64
	ds_read_b128 v[48:51], v89 offset:128
	ds_read_b128 v[52:55], v89 offset:192
	s_waitcnt lgkmcnt(4)
	v_mfma_f32_32x32x16_bf16 v[0:15], v[96:99], v[112:115], v[0:15]
	v_mfma_f32_32x32x16_bf16 v[0:15], v[100:103], v[116:119], v[0:15]
	v_mfma_f32_32x32x16_bf16 v[0:15], v[104:107], v[120:123], v[0:15]
	v_mfma_f32_32x32x16_bf16 v[0:15], v[108:111], v[124:127], v[0:15]
	ds_read_b128 v[128:131], v89 offset:1088
	ds_read_b128 v[132:135], v89 offset:1152
	ds_read_b128 v[136:139], v89 offset:1216
	ds_read_b128 v[140:143], v89 offset:1280
	ds_read_b128 v[72:75], v88 offset:45568
	ds_read_b128 v[76:79], v88 offset:45632
	ds_read_b128 v[80:83], v88 offset:45696
	ds_read_b128 v[84:87], v88 offset:45760
	s_waitcnt lgkmcnt(8)
	v_mfma_f32_16x16x32_bf16 v[24:27], v[40:43], v[56:59], 0
	v_mfma_f32_16x16x32_bf16 v[24:27], v[44:47], v[60:63], v[24:27]
	v_mfma_f32_16x16x32_bf16 v[24:27], v[48:51], v[64:67], v[24:27]
	v_mfma_f32_16x16x32_bf16 v[24:27], v[52:55], v[68:71], v[24:27]
	ds_read_b128 v[40:43], v89 offset:8704
	ds_read_b128 v[44:47], v89 offset:8768
	ds_read_b128 v[48:51], v89 offset:8832
	ds_read_b128 v[52:55], v89 offset:8896
	s_waitcnt lgkmcnt(8)
	v_mfma_f32_16x16x32_bf16 v[28:31], v[128:131], v[56:59], 0
	v_mfma_f32_16x16x32_bf16 v[28:31], v[132:135], v[60:63], v[28:31]
	v_mfma_f32_16x16x32_bf16 v[28:31], v[136:139], v[64:67], v[28:31]
	v_mfma_f32_16x16x32_bf16 v[28:31], v[140:143], v[68:71], v[28:31]
	ds_read_b128 v[128:131], v89 offset:9792
	ds_read_b128 v[132:135], v89 offset:9856
	ds_read_b128 v[136:139], v89 offset:9920
	ds_read_b128 v[140:143], v89 offset:9984
	s_waitcnt lgkmcnt(4)
	v_mfma_f32_16x16x32_bf16 v[32:35], v[40:43], v[56:59], 0
	v_mfma_f32_16x16x32_bf16 v[32:35], v[44:47], v[60:63], v[32:35]
	v_mfma_f32_16x16x32_bf16 v[32:35], v[48:51], v[64:67], v[32:35]
	v_mfma_f32_16x16x32_bf16 v[32:35], v[52:55], v[68:71], v[32:35]
	s_waitcnt lgkmcnt(0)
	v_mfma_f32_16x16x32_bf16 v[36:39], v[128:131], v[56:59], 0
	v_mfma_f32_16x16x32_bf16 v[36:39], v[132:135], v[60:63], v[36:39]
	v_mfma_f32_16x16x32_bf16 v[36:39], v[136:139], v[64:67], v[36:39]
	v_mfma_f32_16x16x32_bf16 v[36:39], v[140:143], v[68:71], v[36:39]
	v_cvt_pk_bf16_f32 v24, v24, v25
	v_cvt_pk_bf16_f32 v25, v26, v27
	v_cvt_pk_bf16_f32 v26, v28, v29
	v_cvt_pk_bf16_f32 v27, v30, v31
	global_store_dwordx4 v90, v[24:27], s[42:43]
	v_cvt_pk_bf16_f32 v32, v32, v33
	v_cvt_pk_bf16_f32 v33, v34, v35
	s_nop 1
	v_cvt_pk_bf16_f32 v34, v36, v37
	v_cvt_pk_bf16_f32 v35, v38, v39
	global_store_dwordx4 v90, v[32:35], s[42:43] offset:64
	s_add_u32 s42, s42, 0x68000
	s_addc_u32 s43, s43, 0
	s_add_i32 s44, s44, 1
	s_waitcnt lgkmcnt(0)
	s_barrier
	s_cmp_eq_u32 s44, 64
	s_cbranch_scc1 .Lsc_oepi

.Lsc_obody5:
	v_cvt_pk_bf16_f32 v16, v0, v1
	v_cvt_pk_bf16_f32 v17, v2, v3
	v_cvt_pk_bf16_f32 v18, v4, v5
	v_cvt_pk_bf16_f32 v19, v6, v7
	v_cvt_pk_bf16_f32 v20, v8, v9
	v_cvt_pk_bf16_f32 v21, v10, v11
	v_cvt_pk_bf16_f32 v22, v12, v13
	v_cvt_pk_bf16_f32 v23, v14, v15
	ds_write_b64 v164, v[16:17] offset:17408
	ds_write_b64 v164, v[18:19] offset:17424
	ds_write_b64 v164, v[20:21] offset:17440
	ds_write_b64 v164, v[22:23] offset:17456
	ds_read_b128 v[128:131], v208 offset:45568
	ds_read_b128 v[132:135], v208 offset:45600
	ds_read_b128 v[136:139], v208 offset:45632
	ds_read_b128 v[140:143], v208 offset:45664
	ds_read_b128 v[96:99], v209 offset:45568
	ds_read_b128 v[100:103], v209 offset:45600
	ds_read_b128 v[104:107], v209 offset:45632
	ds_read_b128 v[108:111], v209 offset:45664
	ds_read_b128 v[112:115], v210 offset:45568
	ds_read_b128 v[116:119], v210 offset:45600
	ds_read_b128 v[120:123], v210 offset:45632
	ds_read_b128 v[124:127], v210 offset:45664
	s_waitcnt lgkmcnt(8)
	v_mul_f32_e32 v0, v0, v128
	v_mul_f32_e32 v1, v1, v129
	v_mul_f32_e32 v2, v2, v130
	v_mul_f32_e32 v3, v3, v131
	v_mul_f32_e32 v4, v4, v132
	v_mul_f32_e32 v5, v5, v133
	v_mul_f32_e32 v6, v6, v134
	v_mul_f32_e32 v7, v7, v135
	v_mul_f32_e32 v8, v8, v136
	v_mul_f32_e32 v9, v9, v137
	v_mul_f32_e32 v10, v10, v138
	v_mul_f32_e32 v11, v11, v139
	v_mul_f32_e32 v12, v12, v140
	v_mul_f32_e32 v13, v13, v141
	v_mul_f32_e32 v14, v14, v142
	v_mul_f32_e32 v15, v15, v143
	ds_read_b128 v[40:43], v89 offset:0
	ds_read_b128 v[44:47], v89 offset:64
	ds_read_b128 v[48:51], v89 offset:128
	ds_read_b128 v[52:55], v89 offset:192
	s_waitcnt lgkmcnt(4)
	v_mfma_f32_32x32x16_bf16 v[0:15], v[96:99], v[112:115], v[0:15]
	v_mfma_f32_32x32x16_bf16 v[0:15], v[100:103], v[116:119], v[0:15]
	v_mfma_f32_32x32x16_bf16 v[0:15], v[104:107], v[120:123], v[0:15]
	v_mfma_f32_32x32x16_bf16 v[0:15], v[108:111], v[124:127], v[0:15]
	ds_read_b128 v[128:131], v89 offset:1088
	ds_read_b128 v[132:135], v89 offset:1152
	ds_read_b128 v[136:139], v89 offset:1216
	ds_read_b128 v[140:143], v89 offset:1280
	ds_read_b128 v[72:75], v88 offset:45568
	ds_read_b128 v[76:79], v88 offset:45632
	ds_read_b128 v[80:83], v88 offset:45696
	ds_read_b128 v[84:87], v88 offset:45760
	s_waitcnt lgkmcnt(8)
	v_mfma_f32_16x16x32_bf16 v[24:27], v[40:43], v[56:59], 0
	v_mfma_f32_16x16x32_bf16 v[24:27], v[44:47], v[60:63], v[24:27]
	v_mfma_f32_16x16x32_bf16 v[24:27], v[48:51], v[64:67], v[24:27]
	v_mfma_f32_16x16x32_bf16 v[24:27], v[52:55], v[68:71], v[24:27]
	ds_read_b128 v[40:43], v89 offset:8704
	ds_read_b128 v[44:47], v89 offset:8768
	ds_read_b128 v[48:51], v89 offset:8832
	ds_read_b128 v[52:55], v89 offset:8896
	s_waitcnt lgkmcnt(8)
	v_mfma_f32_16x16x32_bf16 v[28:31], v[128:131], v[56:59], 0
	v_mfma_f32_16x16x32_bf16 v[28:31], v[132:135], v[60:63], v[28:31]
	v_mfma_f32_16x16x32_bf16 v[28:31], v[136:139], v[64:67], v[28:31]
	v_mfma_f32_16x16x32_bf16 v[28:31], v[140:143], v[68:71], v[28:31]
	ds_read_b128 v[128:131], v89 offset:9792
	ds_read_b128 v[132:135], v89 offset:9856
	ds_read_b128 v[136:139], v89 offset:9920
	ds_read_b128 v[140:143], v89 offset:9984
	s_waitcnt lgkmcnt(4)
	v_mfma_f32_16x16x32_bf16 v[32:35], v[40:43], v[56:59], 0
	v_mfma_f32_16x16x32_bf16 v[32:35], v[44:47], v[60:63], v[32:35]
	v_mfma_f32_16x16x32_bf16 v[32:35], v[48:51], v[64:67], v[32:35]
	v_mfma_f32_16x16x32_bf16 v[32:35], v[52:55], v[68:71], v[32:35]
	s_waitcnt lgkmcnt(0)
	v_mfma_f32_16x16x32_bf16 v[36:39], v[128:131], v[56:59], 0
	v_mfma_f32_16x16x32_bf16 v[36:39], v[132:135], v[60:63], v[36:39]
	v_mfma_f32_16x16x32_bf16 v[36:39], v[136:139], v[64:67], v[36:39]
	v_mfma_f32_16x16x32_bf16 v[36:39], v[140:143], v[68:71], v[36:39]
	v_cvt_pk_bf16_f32 v24, v24, v25
	v_cvt_pk_bf16_f32 v25, v26, v27
	v_cvt_pk_bf16_f32 v26, v28, v29
	v_cvt_pk_bf16_f32 v27, v30, v31
	global_store_dwordx4 v90, v[24:27], s[42:43]
	v_cvt_pk_bf16_f32 v32, v32, v33
	v_cvt_pk_bf16_f32 v33, v34, v35
	s_nop 1
	v_cvt_pk_bf16_f32 v34, v36, v37
	v_cvt_pk_bf16_f32 v35, v38, v39
	global_store_dwordx4 v90, v[32:35], s[42:43] offset:64
	s_add_u32 s42, s42, 0x68000
	s_addc_u32 s43, s43, 0
	s_add_i32 s44, s44, 1
	s_waitcnt lgkmcnt(0)
	s_barrier
	s_branch .Lsc_oloop
.Lsc_oepi:
	ds_read_b128 v[40:43], v89 offset:17408
	ds_read_b128 v[44:47], v89 offset:17472
	ds_read_b128 v[48:51], v89 offset:17536
	ds_read_b128 v[52:55], v89 offset:17600
	ds_read_b128 v[128:131], v89 offset:18496
	ds_read_b128 v[132:135], v89 offset:18560
	ds_read_b128 v[136:139], v89 offset:18624
	ds_read_b128 v[140:143], v89 offset:18688
	s_waitcnt lgkmcnt(4)
	v_mfma_f32_16x16x32_bf16 v[24:27], v[40:43], v[72:75], 0
	v_mfma_f32_16x16x32_bf16 v[24:27], v[44:47], v[76:79], v[24:27]
	v_mfma_f32_16x16x32_bf16 v[24:27], v[48:51], v[80:83], v[24:27]
	v_mfma_f32_16x16x32_bf16 v[24:27], v[52:55], v[84:87], v[24:27]
	ds_read_b128 v[40:43], v89 offset:26112
	ds_read_b128 v[44:47], v89 offset:26176
	ds_read_b128 v[48:51], v89 offset:26240
	ds_read_b128 v[52:55], v89 offset:26304
	s_waitcnt lgkmcnt(4)
	v_mfma_f32_16x16x32_bf16 v[28:31], v[128:131], v[72:75], 0
	v_mfma_f32_16x16x32_bf16 v[28:31], v[132:135], v[76:79], v[28:31]
	v_mfma_f32_16x16x32_bf16 v[28:31], v[136:139], v[80:83], v[28:31]
	v_mfma_f32_16x16x32_bf16 v[28:31], v[140:143], v[84:87], v[28:31]
	ds_read_b128 v[128:131], v89 offset:27200
	ds_read_b128 v[132:135], v89 offset:27264
	ds_read_b128 v[136:139], v89 offset:27328
	ds_read_b128 v[140:143], v89 offset:27392
	s_waitcnt lgkmcnt(4)
	v_mfma_f32_16x16x32_bf16 v[32:35], v[40:43], v[72:75], 0
	v_mfma_f32_16x16x32_bf16 v[32:35], v[44:47], v[76:79], v[32:35]
	v_mfma_f32_16x16x32_bf16 v[32:35], v[48:51], v[80:83], v[32:35]
	v_mfma_f32_16x16x32_bf16 v[32:35], v[52:55], v[84:87], v[32:35]
	s_waitcnt lgkmcnt(0)
	v_mfma_f32_16x16x32_bf16 v[36:39], v[128:131], v[72:75], 0
	v_mfma_f32_16x16x32_bf16 v[36:39], v[132:135], v[76:79], v[36:39]
	v_mfma_f32_16x16x32_bf16 v[36:39], v[136:139], v[80:83], v[36:39]
	v_mfma_f32_16x16x32_bf16 v[36:39], v[140:143], v[84:87], v[36:39]
	s_nop 7
	v_cvt_pk_bf16_f32 v24, v24, v25
	v_cvt_pk_bf16_f32 v25, v26, v27
	v_cvt_pk_bf16_f32 v26, v28, v29
	v_cvt_pk_bf16_f32 v27, v30, v31
	global_store_dwordx4 v90, v[24:27], s[42:43]
	v_cvt_pk_bf16_f32 v32, v32, v33
	v_cvt_pk_bf16_f32 v33, v34, v35
	s_nop 1
	v_cvt_pk_bf16_f32 v34, v36, v37
	v_cvt_pk_bf16_f32 v35, v38, v39
	global_store_dwordx4 v90, v[32:35], s[42:43] offset:64
	s_add_u32 s42, s42, 0x68000
	s_addc_u32 s43, s43, 0
	s_branch .LBB0_176
